# attention steady-state tiles: LDS reads for QK and PV software-pipelined into unused VGPRs v212-v251 instead of read-wait-mfma serial
# speedup vs baseline: 1.0089x; 1.0089x over previous
.LBB0_717:
	s_cmp_ge_i32 s1, s67
	s_cbranch_scc1 .LBB0_721
	ds_read_b128 v[212:215], v201 offset:0
	ds_read_b128 v[216:219], v201 offset:8704
	ds_read_b128 v[220:223], v201 offset:32
	ds_read_b128 v[224:227], v201 offset:8736
	ds_read_b128 v[228:231], v201 offset:64
	ds_read_b128 v[232:235], v201 offset:8768
	ds_read_b128 v[236:239], v201 offset:96
	ds_read_b128 v[240:243], v201 offset:8800
	ds_read_b64_tr_b16 v[244:245], v200 offset:17408
	ds_read_b64_tr_b16 v[246:247], v200 offset:19968
	ds_read_b64_tr_b16 v[248:249], v200 offset:17472
	ds_read_b64_tr_b16 v[250:251], v200 offset:20032
	s_waitcnt lgkmcnt(11)
	v_mfma_f32_32x32x16_bf16 v[96:111], v[212:215], v[128:131], v[16:31]
	s_waitcnt lgkmcnt(10)
	v_mfma_f32_32x32x16_bf16 v[112:127], v[216:219], v[128:131], v[16:31]
	s_waitcnt lgkmcnt(9)
	v_mfma_f32_32x32x16_bf16 v[96:111], v[220:223], v[132:135], v[96:111]
	s_waitcnt lgkmcnt(8)
	v_mfma_f32_32x32x16_bf16 v[112:127], v[224:227], v[132:135], v[112:127]
	s_waitcnt lgkmcnt(7)
	v_mfma_f32_32x32x16_bf16 v[96:111], v[228:231], v[136:139], v[96:111]
	s_waitcnt lgkmcnt(6)
	v_mfma_f32_32x32x16_bf16 v[112:127], v[232:235], v[136:139], v[112:127]
	s_waitcnt lgkmcnt(5)
	v_mfma_f32_32x32x16_bf16 v[96:111], v[236:239], v[140:143], v[96:111]
	s_waitcnt lgkmcnt(4)
	v_mfma_f32_32x32x16_bf16 v[112:127], v[240:243], v[140:143], v[112:127]
	ds_read_b64_tr_b16 v[212:213], v200 offset:17536
	ds_read_b64_tr_b16 v[214:215], v200 offset:20096
	ds_read_b64_tr_b16 v[216:217], v200 offset:17600
	ds_read_b64_tr_b16 v[218:219], v200 offset:20160
	ds_read_b64_tr_b16 v[220:221], v200 offset:22528
	ds_read_b64_tr_b16 v[222:223], v200 offset:25088
	ds_read_b64_tr_b16 v[224:225], v200 offset:22592
	ds_read_b64_tr_b16 v[226:227], v200 offset:25152
	ds_read_b64_tr_b16 v[228:229], v200 offset:22656
	ds_read_b64_tr_b16 v[230:231], v200 offset:25216
	s_nop 3
	v_max3_f32 v0, v96, v97, v112
	v_max3_f32 v2, v98, v99, v113
	s_nop 0
	v_max3_f32 v0, v0, v114, v115
	v_max3_f32 v2, v2, v102, v103
	s_nop 0
	v_max3_f32 v0, v0, v100, v101
	v_max3_f32 v2, v2, v118, v119
	s_nop 0
	v_max3_f32 v0, v0, v116, v117
	v_max3_f32 v2, v2, v106, v107
	s_nop 0
	v_max3_f32 v0, v0, v104, v105
	v_max3_f32 v2, v2, v122, v123
	s_nop 0
	v_max3_f32 v0, v0, v120, v121
	v_max3_f32 v2, v2, v110, v111
	s_nop 0
	v_max3_f32 v0, v0, v108, v109
	v_max3_f32 v2, v2, v126, v127
	s_nop 0
	v_max3_f32 v0, v0, v124, v125
	v_max_f32_e32 v2, v2, v2
	v_max_f32_e32 v0, v0, v0
	v_max_f32_e32 v0, v0, v2
	v_mov_b32_e32 v2, v0
	s_nop 1
	v_permlane32_swap_b32_e32 v0, v2
	v_max_f32_e32 v2, v2, v2
	v_max_f32_e32 v0, v0, v0
	v_max_f32_e32 v0, v0, v2
	v_cmp_lt_f32_e32 vcc, s57, v0
	s_cbranch_vccz .LBB0_720
	v_max_f32_e32 v0, v0, v0
	v_max_f32_e32 v2, 0, v0
	v_exp_f32_e64 v0, -v2
	v_add_f32_e32 v182, v182, v2
	v_xor_b32_e32 v16, 0x80000000, v182
	v_mov_b32_e32 v17, v16
	v_mov_b32_e32 v18, v16
	v_mov_b32_e32 v19, v16
	v_mov_b32_e32 v20, v16
	v_mov_b32_e32 v21, v16
	v_mov_b32_e32 v22, v16
	v_mov_b32_e32 v23, v16
	v_mov_b32_e32 v24, v16
	v_mov_b32_e32 v25, v16
	v_mov_b32_e32 v26, v16
	v_mov_b32_e32 v27, v16
	v_mov_b32_e32 v28, v16
	v_mov_b32_e32 v29, v16
	v_mov_b32_e32 v30, v16
	v_mov_b32_e32 v31, v16
	v_sub_f32_e32 v112, v112, v2
	v_sub_f32_e32 v113, v113, v2
	v_sub_f32_e32 v114, v114, v2
	v_sub_f32_e32 v115, v115, v2
	v_sub_f32_e32 v116, v116, v2
	v_sub_f32_e32 v117, v117, v2
	v_sub_f32_e32 v118, v118, v2
	v_sub_f32_e32 v119, v119, v2
	v_sub_f32_e32 v120, v120, v2
	v_sub_f32_e32 v121, v121, v2
	v_sub_f32_e32 v122, v122, v2
	v_sub_f32_e32 v123, v123, v2
	v_sub_f32_e32 v124, v124, v2
	v_sub_f32_e32 v125, v125, v2
	v_sub_f32_e32 v126, v126, v2
	v_sub_f32_e32 v127, v127, v2
	v_sub_f32_e32 v96, v96, v2
	v_sub_f32_e32 v97, v97, v2
	v_sub_f32_e32 v98, v98, v2
	v_sub_f32_e32 v99, v99, v2
	v_sub_f32_e32 v100, v100, v2
	v_sub_f32_e32 v101, v101, v2
	v_sub_f32_e32 v102, v102, v2
	v_sub_f32_e32 v103, v103, v2
	v_sub_f32_e32 v104, v104, v2
	v_sub_f32_e32 v105, v105, v2
	v_sub_f32_e32 v106, v106, v2
	v_sub_f32_e32 v107, v107, v2
	v_sub_f32_e32 v108, v108, v2
	v_sub_f32_e32 v109, v109, v2
	v_sub_f32_e32 v110, v110, v2
	v_sub_f32_e32 v111, v111, v2
	v_mul_f32_e32 v183, v183, v0
	v_pk_mul_f32 v[94:95], v[94:95], v[0:1] op_sel_hi:[1,0]
	v_pk_mul_f32 v[92:93], v[92:93], v[0:1] op_sel_hi:[1,0]
	v_pk_mul_f32 v[90:91], v[90:91], v[0:1] op_sel_hi:[1,0]
	v_pk_mul_f32 v[88:89], v[88:89], v[0:1] op_sel_hi:[1,0]
	v_pk_mul_f32 v[86:87], v[86:87], v[0:1] op_sel_hi:[1,0]
	v_pk_mul_f32 v[84:85], v[84:85], v[0:1] op_sel_hi:[1,0]
	v_pk_mul_f32 v[82:83], v[82:83], v[0:1] op_sel_hi:[1,0]
	v_pk_mul_f32 v[80:81], v[80:81], v[0:1] op_sel_hi:[1,0]
	v_pk_mul_f32 v[78:79], v[78:79], v[0:1] op_sel_hi:[1,0]
	v_pk_mul_f32 v[76:77], v[76:77], v[0:1] op_sel_hi:[1,0]
	v_pk_mul_f32 v[74:75], v[74:75], v[0:1] op_sel_hi:[1,0]
	v_pk_mul_f32 v[72:73], v[72:73], v[0:1] op_sel_hi:[1,0]
	v_pk_mul_f32 v[70:71], v[70:71], v[0:1] op_sel_hi:[1,0]
	v_pk_mul_f32 v[68:69], v[68:69], v[0:1] op_sel_hi:[1,0]
	v_pk_mul_f32 v[66:67], v[66:67], v[0:1] op_sel_hi:[1,0]
	v_pk_mul_f32 v[64:65], v[64:65], v[0:1] op_sel_hi:[1,0]
	v_pk_mul_f32 v[62:63], v[62:63], v[0:1] op_sel_hi:[1,0]
	v_pk_mul_f32 v[60:61], v[60:61], v[0:1] op_sel_hi:[1,0]
	v_pk_mul_f32 v[58:59], v[58:59], v[0:1] op_sel_hi:[1,0]
	v_pk_mul_f32 v[56:57], v[56:57], v[0:1] op_sel_hi:[1,0]
	v_pk_mul_f32 v[54:55], v[54:55], v[0:1] op_sel_hi:[1,0]
	v_pk_mul_f32 v[52:53], v[52:53], v[0:1] op_sel_hi:[1,0]
	v_pk_mul_f32 v[50:51], v[50:51], v[0:1] op_sel_hi:[1,0]
	v_pk_mul_f32 v[48:49], v[48:49], v[0:1] op_sel_hi:[1,0]
	v_pk_mul_f32 v[46:47], v[46:47], v[0:1] op_sel_hi:[1,0]
	v_pk_mul_f32 v[44:45], v[44:45], v[0:1] op_sel_hi:[1,0]
	v_pk_mul_f32 v[42:43], v[42:43], v[0:1] op_sel_hi:[1,0]
	v_pk_mul_f32 v[40:41], v[40:41], v[0:1] op_sel_hi:[1,0]
	v_pk_mul_f32 v[38:39], v[38:39], v[0:1] op_sel_hi:[1,0]
	v_pk_mul_f32 v[36:37], v[36:37], v[0:1] op_sel_hi:[1,0]
	v_pk_mul_f32 v[34:35], v[34:35], v[0:1] op_sel_hi:[1,0]
	v_pk_mul_f32 v[32:33], v[32:33], v[0:1] op_sel_hi:[1,0]
.LBB0_720:
	s_waitcnt lgkmcnt(9)
	ds_read_b64_tr_b16 v[232:233], v200 offset:22720
	ds_read_b64_tr_b16 v[234:235], v200 offset:25280
	ds_read_b64_tr_b16 v[236:237], v200 offset:27648
	ds_read_b64_tr_b16 v[238:239], v200 offset:30208
	ds_read_b64_tr_b16 v[240:241], v200 offset:27712
	ds_read_b64_tr_b16 v[242:243], v200 offset:30272
	v_exp_f32_e32 v176, v96
	v_exp_f32_e32 v177, v112
	v_exp_f32_e32 v0, v97
	v_exp_f32_e32 v2, v113
	v_exp_f32_e32 v204, v114
	v_add_f32_e32 v3, v177, v176
	v_exp_f32_e32 v8, v115
	v_pk_add_f32 v[4:5], v[2:3], v[0:1]
	v_exp_f32_e32 v3, v98
	v_pk_add_f32 v[4:5], v[4:5], v[4:5] op_sel_hi:[0,1]
	v_exp_f32_e32 v4, v99
	v_exp_f32_e32 v112, v117
	v_add_f32_e32 v9, v204, v3
	v_exp_f32_e32 v114, v123
	v_pk_add_f32 v[6:7], v[8:9], v[4:5]
	v_exp_f32_e32 v5, v100
	v_pk_add_f32 v[6:7], v[6:7], v[6:7] op_sel_hi:[0,1]
	v_exp_f32_e32 v9, v116
	v_exp_f32_e32 v6, v101
	v_exp_f32_e32 v100, v119
	v_exp_f32_e32 v116, v125
	v_add_f32_e32 v113, v9, v5
	v_pk_add_f32 v[10:11], v[112:113], v[6:7]
	v_exp_f32_e32 v7, v102
	v_pk_add_f32 v[10:11], v[10:11], v[10:11] op_sel_hi:[0,1]
	v_exp_f32_e32 v113, v118
	v_exp_f32_e32 v10, v103
	v_exp_f32_e32 v102, v121
	v_exp_f32_e32 v118, v127
	v_add_f32_e32 v101, v113, v7
	v_pk_add_f32 v[12:13], v[100:101], v[10:11]
	v_exp_f32_e32 v11, v104
	v_pk_add_f32 v[12:13], v[12:13], v[12:13] op_sel_hi:[0,1]
	v_exp_f32_e32 v101, v120
	v_exp_f32_e32 v12, v105
	v_cvt_pk_bf16_f32 v98, v5, v6
	v_cvt_pk_bf16_f32 v99, v7, v10
	v_add_f32_e32 v103, v101, v11
	v_pk_add_f32 v[96:97], v[102:103], v[12:13]
	v_exp_f32_e32 v13, v106
	v_pk_add_f32 v[104:105], v[96:97], v[96:97] op_sel_hi:[0,1]
	v_exp_f32_e32 v103, v122
	v_exp_f32_e32 v104, v107
	v_cvt_pk_bf16_f32 v6, v177, v2
	v_cvt_pk_bf16_f32 v7, v204, v8
	v_add_f32_e32 v115, v103, v13
	v_pk_add_f32 v[96:97], v[114:115], v[104:105]
	v_exp_f32_e32 v105, v108
	v_pk_add_f32 v[106:107], v[96:97], v[96:97] op_sel_hi:[0,1]
	v_exp_f32_e32 v115, v124
	v_exp_f32_e32 v106, v109
	v_cvt_pk_bf16_f32 v8, v9, v112
	v_cvt_pk_bf16_f32 v9, v113, v100
	v_add_f32_e32 v117, v115, v105
	v_pk_add_f32 v[96:97], v[116:117], v[106:107]
	v_exp_f32_e32 v107, v110
	v_pk_add_f32 v[108:109], v[96:97], v[96:97] op_sel_hi:[0,1]
	v_exp_f32_e32 v110, v126
	v_exp_f32_e32 v108, v111
	v_cvt_pk_bf16_f32 v2, v101, v102
	v_cvt_pk_bf16_f32 v10, v11, v12
	v_add_f32_e32 v119, v110, v107
	v_pk_add_f32 v[96:97], v[118:119], v[108:109]
	v_cvt_pk_bf16_f32 v11, v13, v104
	v_add_f32_e32 v96, v96, v97
	v_cvt_pk_bf16_f32 v97, v3, v4
	v_cvt_pk_bf16_f32 v3, v103, v114
	v_add_f32_e32 v183, v183, v96
	v_cvt_pk_bf16_f32 v96, v176, v0
	v_cvt_pk_bf16_f32 v12, v105, v106
	v_cvt_pk_bf16_f32 v13, v107, v108
	v_cvt_pk_bf16_f32 v4, v115, v116
	v_cvt_pk_bf16_f32 v5, v110, v118
	s_waitcnt lgkmcnt(3)
	ds_read_b64_tr_b16 v[104:105], v200 offset:27776
	ds_read_b64_tr_b16 v[106:107], v200 offset:30336
	ds_read_b64_tr_b16 v[108:109], v200 offset:27840
	ds_read_b64_tr_b16 v[110:111], v200 offset:30400
	ds_read_b64_tr_b16 v[112:113], v200 offset:32768
	ds_read_b64_tr_b16 v[114:115], v200 offset:35328
	ds_read_b64_tr_b16 v[116:117], v200 offset:32832
	ds_read_b64_tr_b16 v[118:119], v200 offset:35392
	ds_read_b64_tr_b16 v[120:121], v200 offset:32896
	ds_read_b64_tr_b16 v[122:123], v200 offset:35456
	ds_read_b64_tr_b16 v[124:125], v200 offset:32960
	ds_read_b64_tr_b16 v[126:127], v200 offset:35520
	v_mfma_f32_32x32x16_bf16 v[80:95], v[244:247], v[96:99], v[80:95]
	v_mfma_f32_32x32x16_bf16 v[64:79], v[248:251], v[96:99], v[64:79]
	v_mfma_f32_32x32x16_bf16 v[48:63], v[212:215], v[96:99], v[48:63]
	v_mfma_f32_32x32x16_bf16 v[32:47], v[216:219], v[96:99], v[32:47]
	v_mfma_f32_32x32x16_bf16 v[80:95], v[220:223], v[10:13], v[80:95]
	v_mfma_f32_32x32x16_bf16 v[64:79], v[224:227], v[10:13], v[64:79]
	v_mfma_f32_32x32x16_bf16 v[48:63], v[228:231], v[10:13], v[48:63]
	v_mfma_f32_32x32x16_bf16 v[32:47], v[232:235], v[10:13], v[32:47]
	s_waitcnt lgkmcnt(14)
	v_mfma_f32_32x32x16_bf16 v[80:95], v[236:239], v[6:9], v[80:95]
	s_waitcnt lgkmcnt(12)
	v_mfma_f32_32x32x16_bf16 v[64:79], v[240:243], v[6:9], v[64:79]
	s_waitcnt lgkmcnt(10)
	v_mfma_f32_32x32x16_bf16 v[48:63], v[104:107], v[6:9], v[48:63]
	s_waitcnt lgkmcnt(8)
	v_mfma_f32_32x32x16_bf16 v[32:47], v[108:111], v[6:9], v[32:47]
	s_waitcnt lgkmcnt(6)
	v_mfma_f32_32x32x16_bf16 v[80:95], v[112:115], v[2:5], v[80:95]
	s_waitcnt lgkmcnt(4)
	v_mfma_f32_32x32x16_bf16 v[64:79], v[116:119], v[2:5], v[64:79]
	s_waitcnt lgkmcnt(2)
	v_mfma_f32_32x32x16_bf16 v[48:63], v[120:123], v[2:5], v[48:63]
	s_waitcnt lgkmcnt(0)
	v_mfma_f32_32x32x16_bf16 v[32:47], v[124:127], v[2:5], v[32:47]

.LBB0_735:
	v_add_u32_e32 v209, 0x10000, v200
	ds_read_b128 v[212:215], v201 offset:37888
	ds_read_b128 v[216:219], v201 offset:46592
	ds_read_b128 v[220:223], v201 offset:37920
	ds_read_b128 v[224:227], v201 offset:46624
	ds_read_b128 v[228:231], v201 offset:37952
	ds_read_b128 v[232:235], v201 offset:46656
	ds_read_b128 v[236:239], v201 offset:37984
	ds_read_b128 v[240:243], v201 offset:46688
	ds_read_b64_tr_b16 v[244:245], v200 offset:55296
	ds_read_b64_tr_b16 v[246:247], v200 offset:57856
	ds_read_b64_tr_b16 v[248:249], v200 offset:55360
	ds_read_b64_tr_b16 v[250:251], v200 offset:57920
	s_waitcnt lgkmcnt(11)
	v_mfma_f32_32x32x16_bf16 v[96:111], v[212:215], v[128:131], v[16:31]
	s_waitcnt lgkmcnt(10)
	v_mfma_f32_32x32x16_bf16 v[112:127], v[216:219], v[128:131], v[16:31]
	s_waitcnt lgkmcnt(9)
	v_mfma_f32_32x32x16_bf16 v[96:111], v[220:223], v[132:135], v[96:111]
	s_waitcnt lgkmcnt(8)
	v_mfma_f32_32x32x16_bf16 v[112:127], v[224:227], v[132:135], v[112:127]
	s_waitcnt lgkmcnt(7)
	v_mfma_f32_32x32x16_bf16 v[96:111], v[228:231], v[136:139], v[96:111]
	s_waitcnt lgkmcnt(6)
	v_mfma_f32_32x32x16_bf16 v[112:127], v[232:235], v[136:139], v[112:127]
	s_waitcnt lgkmcnt(5)
	v_mfma_f32_32x32x16_bf16 v[96:111], v[236:239], v[140:143], v[96:111]
	s_waitcnt lgkmcnt(4)
	v_mfma_f32_32x32x16_bf16 v[112:127], v[240:243], v[140:143], v[112:127]
	ds_read_b64_tr_b16 v[212:213], v200 offset:55424
	ds_read_b64_tr_b16 v[214:215], v200 offset:57984
	ds_read_b64_tr_b16 v[216:217], v200 offset:55488
	ds_read_b64_tr_b16 v[218:219], v200 offset:58048
	ds_read_b64_tr_b16 v[220:221], v200 offset:60416
	ds_read_b64_tr_b16 v[222:223], v200 offset:62976
	ds_read_b64_tr_b16 v[224:225], v200 offset:60480
	ds_read_b64_tr_b16 v[226:227], v200 offset:63040
	ds_read_b64_tr_b16 v[228:229], v200 offset:60544
	ds_read_b64_tr_b16 v[230:231], v200 offset:63104
	s_nop 3
	v_max3_f32 v0, v96, v97, v112
	v_max3_f32 v2, v98, v99, v113
	s_nop 0
	v_max3_f32 v0, v0, v114, v115
	v_max3_f32 v2, v2, v102, v103
	s_nop 0
	v_max3_f32 v0, v0, v100, v101
	v_max3_f32 v2, v2, v118, v119
	s_nop 0
	v_max3_f32 v0, v0, v116, v117
	v_max3_f32 v2, v2, v106, v107
	s_nop 0
	v_max3_f32 v0, v0, v104, v105
	v_max3_f32 v2, v2, v122, v123
	s_nop 0
	v_max3_f32 v0, v0, v120, v121
	v_max3_f32 v2, v2, v110, v111
	s_nop 0
	v_max3_f32 v0, v0, v108, v109
	v_max3_f32 v2, v2, v126, v127
	s_nop 0
	v_max3_f32 v0, v0, v124, v125
	v_max_f32_e32 v2, v2, v2
	v_max_f32_e32 v0, v0, v0
	v_max_f32_e32 v0, v0, v2
	v_mov_b32_e32 v2, v0
	s_nop 1
	v_permlane32_swap_b32_e32 v0, v2
	v_max_f32_e32 v2, v2, v2
	v_max_f32_e32 v0, v0, v0
	v_max_f32_e32 v0, v0, v2
	v_cmp_lt_f32_e32 vcc, s57, v0
	s_cbranch_vccz .LBB0_737
	v_max_f32_e32 v0, v0, v0
	v_max_f32_e32 v0, 0, v0
	v_add_f32_e32 v182, v182, v0
	v_pk_add_f32 v[96:97], v[96:97], v[0:1] op_sel_hi:[1,0] neg_lo:[0,1] neg_hi:[0,1]
	v_pk_add_f32 v[112:113], v[112:113], v[0:1] op_sel_hi:[1,0] neg_lo:[0,1] neg_hi:[0,1]
	v_pk_add_f32 v[98:99], v[98:99], v[0:1] op_sel_hi:[1,0] neg_lo:[0,1] neg_hi:[0,1]
	v_pk_add_f32 v[114:115], v[114:115], v[0:1] op_sel_hi:[1,0] neg_lo:[0,1] neg_hi:[0,1]
	v_pk_add_f32 v[100:101], v[100:101], v[0:1] op_sel_hi:[1,0] neg_lo:[0,1] neg_hi:[0,1]
	v_pk_add_f32 v[116:117], v[116:117], v[0:1] op_sel_hi:[1,0] neg_lo:[0,1] neg_hi:[0,1]
	v_pk_add_f32 v[102:103], v[102:103], v[0:1] op_sel_hi:[1,0] neg_lo:[0,1] neg_hi:[0,1]
	v_pk_add_f32 v[118:119], v[118:119], v[0:1] op_sel_hi:[1,0] neg_lo:[0,1] neg_hi:[0,1]
	v_pk_add_f32 v[104:105], v[104:105], v[0:1] op_sel_hi:[1,0] neg_lo:[0,1] neg_hi:[0,1]
	v_pk_add_f32 v[120:121], v[120:121], v[0:1] op_sel_hi:[1,0] neg_lo:[0,1] neg_hi:[0,1]
	v_pk_add_f32 v[106:107], v[106:107], v[0:1] op_sel_hi:[1,0] neg_lo:[0,1] neg_hi:[0,1]
	v_pk_add_f32 v[122:123], v[122:123], v[0:1] op_sel_hi:[1,0] neg_lo:[0,1] neg_hi:[0,1]
	v_pk_add_f32 v[108:109], v[108:109], v[0:1] op_sel_hi:[1,0] neg_lo:[0,1] neg_hi:[0,1]
	v_pk_add_f32 v[124:125], v[124:125], v[0:1] op_sel_hi:[1,0] neg_lo:[0,1] neg_hi:[0,1]
	v_pk_add_f32 v[110:111], v[110:111], v[0:1] op_sel_hi:[1,0] neg_lo:[0,1] neg_hi:[0,1]
	v_pk_add_f32 v[126:127], v[126:127], v[0:1] op_sel_hi:[1,0] neg_lo:[0,1] neg_hi:[0,1]
	v_exp_f32_e64 v0, -v0
	v_xor_b32_e32 v16, 0x80000000, v182
	v_mov_b32_e32 v17, v16
	v_mov_b32_e32 v18, v16
	v_mov_b32_e32 v19, v16
	v_mov_b32_e32 v20, v16
	v_mov_b32_e32 v21, v16
	v_mov_b32_e32 v22, v16
	v_mov_b32_e32 v23, v16
	v_mov_b32_e32 v24, v16
	v_mov_b32_e32 v25, v16
	v_mov_b32_e32 v26, v16
	v_mov_b32_e32 v27, v16
	v_mov_b32_e32 v28, v16
	v_mov_b32_e32 v29, v16
	v_mov_b32_e32 v30, v16
	v_mov_b32_e32 v31, v16
	v_mul_f32_e32 v183, v183, v0
	v_pk_mul_f32 v[94:95], v[94:95], v[0:1] op_sel_hi:[1,0]
	v_pk_mul_f32 v[92:93], v[92:93], v[0:1] op_sel_hi:[1,0]
	v_pk_mul_f32 v[90:91], v[90:91], v[0:1] op_sel_hi:[1,0]
	v_pk_mul_f32 v[88:89], v[88:89], v[0:1] op_sel_hi:[1,0]
	v_pk_mul_f32 v[86:87], v[86:87], v[0:1] op_sel_hi:[1,0]
	v_pk_mul_f32 v[84:85], v[84:85], v[0:1] op_sel_hi:[1,0]
	v_pk_mul_f32 v[82:83], v[82:83], v[0:1] op_sel_hi:[1,0]
	v_pk_mul_f32 v[80:81], v[80:81], v[0:1] op_sel_hi:[1,0]
	v_pk_mul_f32 v[78:79], v[78:79], v[0:1] op_sel_hi:[1,0]
	v_pk_mul_f32 v[76:77], v[76:77], v[0:1] op_sel_hi:[1,0]
	v_pk_mul_f32 v[74:75], v[74:75], v[0:1] op_sel_hi:[1,0]
	v_pk_mul_f32 v[72:73], v[72:73], v[0:1] op_sel_hi:[1,0]
	v_pk_mul_f32 v[70:71], v[70:71], v[0:1] op_sel_hi:[1,0]
	v_pk_mul_f32 v[68:69], v[68:69], v[0:1] op_sel_hi:[1,0]
	v_pk_mul_f32 v[66:67], v[66:67], v[0:1] op_sel_hi:[1,0]
	v_pk_mul_f32 v[64:65], v[64:65], v[0:1] op_sel_hi:[1,0]
	v_pk_mul_f32 v[62:63], v[62:63], v[0:1] op_sel_hi:[1,0]
	v_pk_mul_f32 v[60:61], v[60:61], v[0:1] op_sel_hi:[1,0]
	v_pk_mul_f32 v[58:59], v[58:59], v[0:1] op_sel_hi:[1,0]
	v_pk_mul_f32 v[56:57], v[56:57], v[0:1] op_sel_hi:[1,0]
	v_pk_mul_f32 v[54:55], v[54:55], v[0:1] op_sel_hi:[1,0]
	v_pk_mul_f32 v[52:53], v[52:53], v[0:1] op_sel_hi:[1,0]
	v_pk_mul_f32 v[50:51], v[50:51], v[0:1] op_sel_hi:[1,0]
	v_pk_mul_f32 v[48:49], v[48:49], v[0:1] op_sel_hi:[1,0]
	v_pk_mul_f32 v[46:47], v[46:47], v[0:1] op_sel_hi:[1,0]
	v_pk_mul_f32 v[44:45], v[44:45], v[0:1] op_sel_hi:[1,0]
	v_pk_mul_f32 v[42:43], v[42:43], v[0:1] op_sel_hi:[1,0]
	v_pk_mul_f32 v[40:41], v[40:41], v[0:1] op_sel_hi:[1,0]
	v_pk_mul_f32 v[38:39], v[38:39], v[0:1] op_sel_hi:[1,0]
	v_pk_mul_f32 v[36:37], v[36:37], v[0:1] op_sel_hi:[1,0]
	v_pk_mul_f32 v[34:35], v[34:35], v[0:1] op_sel_hi:[1,0]
	v_pk_mul_f32 v[32:33], v[32:33], v[0:1] op_sel_hi:[1,0]
.LBB0_737:
	s_waitcnt lgkmcnt(9)
	ds_read_b64_tr_b16 v[232:233], v200 offset:60608
	ds_read_b64_tr_b16 v[234:235], v200 offset:63168
	ds_read_b64_tr_b16 v[236:237], v209 offset:0
	ds_read_b64_tr_b16 v[238:239], v209 offset:2560
	ds_read_b64_tr_b16 v[240:241], v209 offset:64
	ds_read_b64_tr_b16 v[242:243], v209 offset:2624
	v_exp_f32_e32 v176, v96
	v_exp_f32_e32 v177, v112
	v_exp_f32_e32 v0, v97
	v_exp_f32_e32 v2, v113
	v_exp_f32_e32 v204, v114
	v_add_f32_e32 v3, v177, v176
	v_exp_f32_e32 v8, v115
	v_pk_add_f32 v[4:5], v[2:3], v[0:1]
	v_exp_f32_e32 v3, v98
	v_pk_add_f32 v[4:5], v[4:5], v[4:5] op_sel_hi:[0,1]
	v_exp_f32_e32 v4, v99
	v_exp_f32_e32 v112, v117
	v_add_f32_e32 v9, v204, v3
	v_exp_f32_e32 v114, v123
	v_pk_add_f32 v[6:7], v[8:9], v[4:5]
	v_exp_f32_e32 v5, v100
	v_pk_add_f32 v[6:7], v[6:7], v[6:7] op_sel_hi:[0,1]
	v_exp_f32_e32 v9, v116
	v_exp_f32_e32 v6, v101
	v_exp_f32_e32 v100, v119
	v_exp_f32_e32 v116, v125
	v_add_f32_e32 v113, v9, v5
	v_pk_add_f32 v[10:11], v[112:113], v[6:7]
	v_exp_f32_e32 v7, v102
	v_pk_add_f32 v[10:11], v[10:11], v[10:11] op_sel_hi:[0,1]
	v_exp_f32_e32 v113, v118
	v_exp_f32_e32 v10, v103
	v_exp_f32_e32 v102, v121
	v_exp_f32_e32 v118, v127
	v_add_f32_e32 v101, v113, v7
	v_pk_add_f32 v[12:13], v[100:101], v[10:11]
	v_exp_f32_e32 v11, v104
	v_pk_add_f32 v[12:13], v[12:13], v[12:13] op_sel_hi:[0,1]
	v_exp_f32_e32 v101, v120
	v_exp_f32_e32 v12, v105
	v_cvt_pk_bf16_f32 v98, v5, v6
	v_cvt_pk_bf16_f32 v99, v7, v10
	v_add_f32_e32 v103, v101, v11
	v_pk_add_f32 v[96:97], v[102:103], v[12:13]
	v_exp_f32_e32 v13, v106
	v_pk_add_f32 v[104:105], v[96:97], v[96:97] op_sel_hi:[0,1]
	v_exp_f32_e32 v103, v122
	v_exp_f32_e32 v104, v107
	v_cvt_pk_bf16_f32 v6, v177, v2
	v_cvt_pk_bf16_f32 v7, v204, v8
	v_add_f32_e32 v115, v103, v13
	v_pk_add_f32 v[96:97], v[114:115], v[104:105]
	v_exp_f32_e32 v105, v108
	v_pk_add_f32 v[106:107], v[96:97], v[96:97] op_sel_hi:[0,1]
	v_exp_f32_e32 v115, v124
	v_exp_f32_e32 v106, v109
	v_cvt_pk_bf16_f32 v8, v9, v112
	v_cvt_pk_bf16_f32 v9, v113, v100
	v_add_f32_e32 v117, v115, v105
	v_pk_add_f32 v[96:97], v[116:117], v[106:107]
	v_exp_f32_e32 v107, v110
	v_pk_add_f32 v[108:109], v[96:97], v[96:97] op_sel_hi:[0,1]
	v_exp_f32_e32 v110, v126
	v_exp_f32_e32 v108, v111
	v_cvt_pk_bf16_f32 v2, v101, v102
	v_cvt_pk_bf16_f32 v10, v11, v12
	v_add_f32_e32 v119, v110, v107
	v_pk_add_f32 v[96:97], v[118:119], v[108:109]
	v_cvt_pk_bf16_f32 v11, v13, v104
	v_add_f32_e32 v96, v96, v97
	v_cvt_pk_bf16_f32 v97, v3, v4
	v_cvt_pk_bf16_f32 v3, v103, v114
	v_add_f32_e32 v183, v183, v96
	v_cvt_pk_bf16_f32 v96, v176, v0
	v_cvt_pk_bf16_f32 v12, v105, v106
	v_cvt_pk_bf16_f32 v13, v107, v108
	v_cvt_pk_bf16_f32 v4, v115, v116
	v_cvt_pk_bf16_f32 v5, v110, v118
	s_waitcnt lgkmcnt(3)
	ds_read_b64_tr_b16 v[104:105], v209 offset:128
	ds_read_b64_tr_b16 v[106:107], v209 offset:2688
	ds_read_b64_tr_b16 v[108:109], v209 offset:192
	ds_read_b64_tr_b16 v[110:111], v209 offset:2752
	ds_read_b64_tr_b16 v[112:113], v209 offset:5120
	ds_read_b64_tr_b16 v[114:115], v209 offset:7680
	ds_read_b64_tr_b16 v[116:117], v209 offset:5184
	ds_read_b64_tr_b16 v[118:119], v209 offset:7744
	ds_read_b64_tr_b16 v[120:121], v209 offset:5248
	ds_read_b64_tr_b16 v[122:123], v209 offset:7808
	ds_read_b64_tr_b16 v[124:125], v209 offset:5312
	ds_read_b64_tr_b16 v[126:127], v209 offset:7872
	v_mfma_f32_32x32x16_bf16 v[80:95], v[244:247], v[96:99], v[80:95]
	v_mfma_f32_32x32x16_bf16 v[64:79], v[248:251], v[96:99], v[64:79]
	v_mfma_f32_32x32x16_bf16 v[48:63], v[212:215], v[96:99], v[48:63]
	v_mfma_f32_32x32x16_bf16 v[32:47], v[216:219], v[96:99], v[32:47]
	v_mfma_f32_32x32x16_bf16 v[80:95], v[220:223], v[10:13], v[80:95]
	v_mfma_f32_32x32x16_bf16 v[64:79], v[224:227], v[10:13], v[64:79]
	v_mfma_f32_32x32x16_bf16 v[48:63], v[228:231], v[10:13], v[48:63]
	v_mfma_f32_32x32x16_bf16 v[32:47], v[232:235], v[10:13], v[32:47]
	s_waitcnt lgkmcnt(14)
	v_mfma_f32_32x32x16_bf16 v[80:95], v[236:239], v[6:9], v[80:95]
	s_waitcnt lgkmcnt(12)
	v_mfma_f32_32x32x16_bf16 v[64:79], v[240:243], v[6:9], v[64:79]
	s_waitcnt lgkmcnt(10)
	v_mfma_f32_32x32x16_bf16 v[48:63], v[104:107], v[6:9], v[48:63]
	s_waitcnt lgkmcnt(8)
	v_mfma_f32_32x32x16_bf16 v[32:47], v[108:111], v[6:9], v[32:47]
	s_waitcnt lgkmcnt(6)
	v_mfma_f32_32x32x16_bf16 v[80:95], v[112:115], v[2:5], v[80:95]
	s_waitcnt lgkmcnt(4)
	v_mfma_f32_32x32x16_bf16 v[64:79], v[116:119], v[2:5], v[64:79]
	s_waitcnt lgkmcnt(2)
	v_mfma_f32_32x32x16_bf16 v[48:63], v[120:123], v[2:5], v[48:63]
	s_waitcnt lgkmcnt(0)
	v_mfma_f32_32x32x16_bf16 v[32:47], v[124:127], v[2:5], v[32:47]
	s_andn2_b64 vcc, exec, s[36:37]
	s_cbranch_vccnz .LBB0_708
